# row pass A: kv-norm gain vector kept in registers instead of one reload plus vmcnt(0) per row
# baseline (speedup 1.0000x reference)
.LBB0_765:
	s_add_i32 s74, s18, 0x4000
	s_cmpk_gt_i32 s74, 0x3fff
	s_cselect_b64 s[78:79], -1, 0
	s_and_b32 s0, s74, 0xfff
	s_cmpk_lt_i32 s74, 0x4000
	s_cselect_b32 s0, s0, s64
	s_add_i32 s72, s92, s18
	v_lshl_add_u64 v[0:1], s[28:29], 0, v[18:19]
	s_lshl_b32 s10, s0, 7
	s_add_i32 s50, s72, 0x4000
	v_add_co_u32_e32 v0, vcc, 0x9211000, v0
	s_cmpk_lt_i32 s50, 0x4200
	s_nop 0
	v_addc_co_u32_e32 v1, vcc, 0, v1, vcc
	s_waitcnt lgkmcnt(0)
	v_lshl_add_u64 v[2:3], s[28:29], 0, v[8:9]
	s_cselect_b64 s[76:77], -1, 0
	v_add_co_u32_e32 v2, vcc, 0x9211000, v2
	s_and_b64 s[0:1], s[76:77], exec
	s_nop 0
	v_addc_co_u32_e32 v3, vcc, 0, v3, vcc
	global_load_dword v84, v[0:1], off offset:512
	global_load_dword v83, v[0:1], off offset:768
	global_load_dword v82, v[0:1], off offset:1024
	global_load_ushort v78, v[2:3], off offset:1280
	global_load_ushort v79, v[2:3], off offset:1312
	v_lshl_add_u64 v[0:1], v[10:11], 0, s[10:11]
	s_cselect_b32 s10, s50, s74
	s_mul_i32 s0, s10, 0x600
	s_mul_hi_i32 s1, s10, 0x600
	s_add_u32 s0, s60, s0
	s_addc_u32 s1, s62, s1
	v_lshl_add_u64 v[2:3], s[0:1], 0, v[14:15]
	v_lshl_add_u64 v[28:29], v[2:3], 0, v[24:25]
	global_load_dword v81, v[0:1], off
	global_load_dword v80, v[0:1], off offset:64
	global_load_dwordx2 v[34:35], v[2:3], off
	global_load_dword v77, v[28:29], off offset:512
	global_load_dword v76, v[28:29], off offset:768
	global_load_dword v74, v[28:29], off offset:1024
	global_load_ushort v71, v46, s[0:1] offset:1280
	global_load_ushort v72, v46, s[0:1] offset:1312
	s_and_b32 s1, s10, 3
	s_and_b32 s0, s10, 0xfff
	s_bitset1_b32 s1, 12
	s_cmpk_lt_i32 s10, 0x4000
	s_cselect_b32 s0, s0, s1
	s_add_i32 s46, s86, s18
	s_lshl_b32 s10, s0, 7
	s_add_i32 s44, s46, 0x4000
	s_cmpk_lt_i32 s44, 0x4200
	s_cselect_b64 s[68:69], -1, 0
	s_and_b64 s[0:1], s[68:69], exec
	v_lshl_add_u64 v[0:1], v[10:11], 0, s[10:11]
	s_cselect_b32 s10, s44, s74
	s_mul_i32 s0, s10, 0x600
	s_mul_hi_i32 s1, s10, 0x600
	s_add_u32 s0, s60, s0
	s_addc_u32 s1, s62, s1
	s_and_b32 s13, s10, 3
	s_and_b32 s12, s10, 0xfff
	s_bitset1_b32 s13, 12
	s_cmpk_lt_i32 s10, 0x4000
	s_cselect_b32 s10, s12, s13
	s_lshl_b32 s10, s10, 7
	v_lshl_add_u64 v[2:3], s[0:1], 0, v[14:15]
	v_lshl_add_u64 v[30:31], v[10:11], 0, s[10:11]
	v_lshl_add_u64 v[28:29], v[2:3], 0, v[24:25]
	global_load_dwordx2 v[32:33], v[2:3], off
	global_load_dword v70, v[28:29], off offset:512
	global_load_dword v69, v[28:29], off offset:768
	global_load_dword v68, v[28:29], off offset:1024
	global_load_dword v65, v[30:31], off
	global_load_dword v64, v[30:31], off offset:64
	v_lshl_add_u64 v[30:31], s[28:29], 0, v[26:27]
	global_load_dwordx2 v[38:39], v[30:31], off
	s_mul_i32 s10, s57, 24
	s_add_i32 s40, s10, s18
	s_add_i32 s38, s40, 0x4000
	s_cmpk_lt_i32 s38, 0x4200
	s_cselect_b64 s[48:49], -1, 0
	s_and_b64 s[12:13], s[48:49], exec
	s_cselect_b32 s10, s38, s74
	s_mul_i32 s12, s10, 0x600
	s_mul_hi_i32 s13, s10, 0x600
	s_add_u32 s12, s60, s12
	s_addc_u32 s13, s62, s13
	s_and_b32 s34, s10, 3
	s_and_b32 s19, s10, 0xfff
	s_bitset1_b32 s34, 12
	s_cmpk_lt_i32 s10, 0x4000
	s_cselect_b32 s10, s19, s34
	s_add_i32 s36, s87, s18
	s_lshl_b32 s10, s10, 7
	s_add_i32 s34, s36, 0x4000
	s_cmpk_lt_i32 s34, 0x4200
	s_cselect_b64 s[42:43], -1, 0
	s_and_b64 s[52:53], s[42:43], exec
	v_lshl_add_u64 v[36:37], v[10:11], 0, s[10:11]
	s_cselect_b32 s10, s34, s74
	s_mul_i32 s35, s10, 0x600
	v_lshl_add_u64 v[2:3], s[12:13], 0, v[14:15]
	s_mul_hi_i32 s19, s10, 0x600
	s_add_u32 s52, s60, s35
	v_lshl_add_u64 v[28:29], v[2:3], 0, v[24:25]
	global_load_dwordx2 v[30:31], v[2:3], off
	global_load_dword v63, v[28:29], off offset:512
	global_load_dword v62, v[28:29], off offset:768
	global_load_dword v61, v[28:29], off offset:1024
	global_load_dword v58, v[36:37], off
	global_load_dword v57, v[36:37], off offset:64
	s_addc_u32 s53, s62, s19
	global_load_dword v75, v[0:1], off
	global_load_dword v73, v[0:1], off offset:64
	global_load_ushort v66, v46, s[0:1] offset:1280
	global_load_ushort v67, v46, s[0:1] offset:1312
	global_load_ushort v59, v46, s[12:13] offset:1280
	global_load_ushort v60, v46, s[12:13] offset:1312
	global_load_ushort v50, v46, s[52:53] offset:1280
	global_load_ushort v51, v46, s[52:53] offset:1312
	s_and_b32 s1, s10, 3
	s_and_b32 s0, s10, 0xfff
	s_bitset1_b32 s1, 12
	s_cmpk_lt_i32 s10, 0x4000
	s_cselect_b32 s0, s0, s1
	s_lshl_b32 s10, s0, 7
	v_lshl_add_u64 v[2:3], s[52:53], 0, v[14:15]
	v_lshl_add_u64 v[0:1], v[10:11], 0, s[10:11]
	v_lshl_add_u64 v[36:37], v[2:3], 0, v[24:25]
	global_load_dwordx2 v[28:29], v[2:3], off
	global_load_dword v56, v[36:37], off offset:512
	global_load_dword v55, v[36:37], off offset:768
	global_load_dword v54, v[36:37], off offset:1024
	global_load_dword v53, v[0:1], off
	global_load_dword v52, v[0:1], off offset:64
	s_nop 0
	global_load_dwordx4 v[0:3], v[12:13], off
	s_mov_b64 s[0:1], -1
	s_and_b64 vcc, exec, s[78:79]
	s_waitcnt vmcnt(0)
	v_mov_b32_e32 v96, v0
	v_mov_b32_e32 v97, v1
	v_mov_b32_e32 v98, v2
	v_mov_b32_e32 v99, v3
	v_lshlrev_b32_e32 v37, 16, v39
	v_lshlrev_b32_e32 v36, 16, v38
	v_and_b32_e32 v39, 0xffff0000, v39
	v_and_b32_e32 v38, 0xffff0000, v38
	v_pk_mul_f32 v[86:87], v[38:39], v[38:39]
	s_nop 0
	v_pk_fma_f32 v[86:87], v[36:37], v[36:37], v[86:87]
	s_nop 0
	v_add_f32_e32 v85, v86, v87
	ds_bpermute_b32 v86, v40, v85
	s_waitcnt lgkmcnt(0)
	v_add_f32_e32 v85, v85, v86
	ds_bpermute_b32 v86, v41, v85
	s_waitcnt lgkmcnt(0)
	v_add_f32_e32 v85, v85, v86
	ds_bpermute_b32 v86, v42, v85
	s_waitcnt lgkmcnt(0)
	v_add_f32_e32 v85, v85, v86
	ds_bpermute_b32 v86, v43, v85
	s_waitcnt lgkmcnt(0)
	v_add_f32_e32 v85, v85, v86
	ds_bpermute_b32 v86, v44, v85
	s_waitcnt lgkmcnt(0)
	v_add_f32_e32 v85, v85, v86
	ds_bpermute_b32 v86, v45, v85
	s_cbranch_vccz .LBB0_767
	s_mov_b32 s19, s11
	s_lshl_b64 s[0:1], s[18:19], 10
	s_add_u32 s12, s66, s0
	s_addc_u32 s13, s67, s1
	s_mov_b32 s75, s11
	s_mov_b64 s[0:1], 0

.LBB0_780:
	s_waitcnt lgkmcnt(0)
	v_mov_b32_e32 v0, v96
	v_mov_b32_e32 v1, v97
	v_mov_b32_e32 v2, v98
	v_mov_b32_e32 v3, v99
	v_lshlrev_b32_e32 v37, 16, v35
	v_lshlrev_b32_e32 v36, 16, v34
	v_and_b32_e32 v35, 0xffff0000, v35
	v_and_b32_e32 v34, 0xffff0000, v34
	v_pk_mul_f32 v[38:39], v[34:35], v[34:35]
	s_cmpk_gt_i32 s50, 0x3fff
	v_pk_fma_f32 v[38:39], v[36:37], v[36:37], v[38:39]
	s_cselect_b64 s[74:75], -1, 0
	v_add_f32_e32 v38, v38, v39
	ds_bpermute_b32 v39, v40, v38
	s_cmpk_lt_i32 s50, 0x4000
	s_mov_b64 s[0:1], -1
	s_waitcnt lgkmcnt(0)
	v_add_f32_e32 v38, v38, v39
	ds_bpermute_b32 v39, v41, v38
	s_waitcnt lgkmcnt(0)
	v_add_f32_e32 v38, v38, v39
	ds_bpermute_b32 v39, v42, v38
	s_waitcnt lgkmcnt(0)
	v_add_f32_e32 v38, v38, v39
	ds_bpermute_b32 v39, v43, v38
	s_waitcnt lgkmcnt(0)
	v_add_f32_e32 v38, v38, v39
	ds_bpermute_b32 v39, v44, v38
	s_waitcnt lgkmcnt(0)
	v_add_f32_e32 v38, v38, v39
	ds_bpermute_b32 v39, v45, v38
	s_cbranch_scc1 .LBB0_782
	s_mov_b32 s73, s11
	s_lshl_b64 s[0:1], s[72:73], 10
	s_add_u32 s12, s66, s0
	s_addc_u32 s13, s67, s1
	s_mov_b32 s51, s11
	s_mov_b64 s[0:1], 0

.LBB0_784:
	s_waitcnt lgkmcnt(0)
	v_add_f32_e32 v38, v38, v39
	v_fmamk_f32 v38, v38, 0x3b800000, v47
	v_mul_f32_e32 v39, 0x4f800000, v38
	v_cmp_gt_f32_e32 vcc, s89, v38
	v_and_b32_e32 v81, 0xffff0000, v77
	v_and_b32_e32 v83, 0xffff0000, v76
	v_cndmask_b32_e32 v38, v38, v39, vcc
	v_sqrt_f32_e32 v39, v38
	v_lshlrev_b32_e32 v82, 16, v76
	v_mul_f32_e32 v76, v83, v83
	v_fmac_f32_e32 v76, v82, v82
	v_add_u32_e32 v78, -1, v39
	v_fma_f32 v80, -v78, v39, v38
	v_add_u32_e32 v79, 1, v39
	v_cmp_ge_f32_e64 s[0:1], 0, v80
	v_lshlrev_b32_e32 v80, 16, v77
	v_mul_f32_e32 v77, v81, v81
	v_cndmask_b32_e64 v78, v39, v78, s[0:1]
	v_fma_f32 v39, -v79, v39, v38
	v_cmp_lt_f32_e64 s[0:1], 0, v39
	v_fmac_f32_e32 v77, v80, v80
	v_lshlrev_b32_e32 v84, 16, v74
	v_cndmask_b32_e64 v39, v78, v79, s[0:1]
	v_mul_f32_e32 v78, 0x37800000, v39
	v_cndmask_b32_e32 v39, v39, v78, vcc
	v_cmp_class_f32_e32 vcc, v38, v48
	v_and_b32_e32 v74, 0xffff0000, v74
	v_add_f32_e32 v76, v77, v76
	v_cndmask_b32_e32 v38, v39, v38, vcc
	v_div_scale_f32 v39, s[0:1], v38, v38, 1.0
	v_rcp_f32_e32 v78, v39
	v_mul_f32_e32 v77, v74, v74
	v_fmac_f32_e32 v77, v84, v84
	v_add_f32_e32 v76, v76, v77
	v_fma_f32 v79, -v39, v78, 1.0
	ds_bpermute_b32 v77, v40, v76
	v_fmac_f32_e32 v78, v79, v78
	v_div_scale_f32 v79, vcc, 1.0, v38, 1.0
	v_mul_f32_e32 v85, v79, v78
	v_fma_f32 v86, -v39, v85, v79
	v_fmac_f32_e32 v85, v86, v78
	v_fma_f32 v39, -v39, v85, v79
	s_waitcnt lgkmcnt(0)
	v_add_f32_e32 v79, v76, v77
	ds_bpermute_b32 v86, v41, v79
	v_div_fmas_f32 v39, v39, v78, v85
	v_mov_b32_e32 v76, v36
	v_div_fixup_f32 v38, v39, v38, 1.0
	v_mov_b32_e32 v77, v34
	s_waitcnt lgkmcnt(0)
	v_add_f32_e32 v36, v79, v86
	ds_bpermute_b32 v39, v42, v36
	v_mov_b32_e32 v34, v37
	s_waitcnt lgkmcnt(0)
	v_add_f32_e32 v36, v36, v39
	ds_bpermute_b32 v37, v43, v36
	v_pk_mul_f32 v[76:77], v[38:39], v[76:77] op_sel_hi:[0,1]
	v_pk_mul_f32 v[34:35], v[38:39], v[34:35] op_sel_hi:[0,1]
	v_pk_mul_f32 v[2:3], v[2:3], v[34:35]
	v_pk_mul_f32 v[0:1], v[0:1], v[76:77]
	v_lshl_add_u64 v[34:35], v[6:7], 2, s[12:13]
	global_store_dwordx4 v[34:35], v[0:3], off
	s_waitcnt lgkmcnt(0)
	v_add_f32_e32 v35, v36, v37
	ds_bpermute_b32 v36, v44, v35
	v_bfe_u32 v34, v0, 16, 1
	v_add3_u32 v0, v0, v34, s90
	v_bfe_u32 v34, v1, 16, 1
	v_add3_u32 v1, v1, v34, s90
	s_waitcnt lgkmcnt(0)
	v_add_f32_e32 v34, v35, v36
	ds_bpermute_b32 v35, v45, v34
	v_lshrrev_b32_e32 v0, 16, v0
	v_and_or_b32 v0, v1, s88, v0
	v_bfe_u32 v1, v2, 16, 1
	v_add3_u32 v1, v2, v1, s90
	s_waitcnt lgkmcnt(0)
	v_add_f32_e32 v2, v34, v35
	v_fmamk_f32 v2, v2, 0x3b2aaaab, v47
	v_mul_f32_e32 v34, 0x4f800000, v2
	v_cmp_gt_f32_e32 vcc, s89, v2
	v_bfe_u32 v35, v3, 16, 1
	v_lshrrev_b32_e32 v1, 16, v1
	v_cndmask_b32_e32 v2, v2, v34, vcc
	v_sqrt_f32_e32 v34, v2
	v_add3_u32 v3, v3, v35, s90
	v_and_or_b32 v1, v3, s88, v1
	v_add_u32_e32 v3, -1, v34
	v_fma_f32 v35, -v3, v34, v2
	v_cmp_ge_f32_e64 s[0:1], 0, v35
	v_add_u32_e32 v35, 1, v34
	s_nop 0
	v_cndmask_b32_e64 v3, v34, v3, s[0:1]
	v_fma_f32 v34, -v35, v34, v2
	v_cmp_lt_f32_e64 s[0:1], 0, v34
	s_nop 1
	v_cndmask_b32_e64 v3, v3, v35, s[0:1]
	v_mul_f32_e32 v34, 0x37800000, v3
	v_cndmask_b32_e32 v3, v3, v34, vcc
	v_cmp_class_f32_e32 vcc, v2, v48
	s_nop 1
	v_cndmask_b32_e32 v34, v3, v2, vcc
	v_div_scale_f32 v35, s[0:1], v34, v34, 1.0
	v_rcp_f32_e32 v36, v35
	s_lshl_b64 s[0:1], s[50:51], 9
	v_lshl_add_u64 v[2:3], v[16:17], 0, s[0:1]
	global_store_dwordx2 v[2:3], v[0:1], off
	v_fma_f32 v0, -v35, v36, 1.0
	v_fmac_f32_e32 v36, v0, v36
	v_div_scale_f32 v0, vcc, 1.0, v34, 1.0
	v_mul_f32_e32 v1, v0, v36
	v_fma_f32 v2, -v35, v1, v0
	v_fmac_f32_e32 v1, v2, v36
	v_fma_f32 v0, -v35, v1, v0
	v_div_fmas_f32 v0, v0, v36, v1
	v_div_fixup_f32 v1, v0, v34, 1.0
	v_mul_f32_e32 v0, v1, v80
	v_bfe_u32 v3, v0, 16, 1
	v_mul_f32_e32 v2, v1, v81
	v_add3_u32 v0, v0, v3, s90
	v_lshrrev_b32_e32 v3, 16, v0
	v_bfe_u32 v0, v2, 16, 1
	v_lshlrev_b32_e32 v36, 16, v72
	v_add3_u32 v2, v2, v0, s90
	v_lshlrev_b32_e32 v0, 16, v71
	v_mul_f32_e32 v37, v73, v36
	v_mul_f32_e32 v36, v75, v36
	v_fma_f32 v37, v75, v0, -v37
	v_fmac_f32_e32 v36, v73, v0
	v_cndmask_b32_e64 v0, v36, v37, s[2:3]
	v_mul_f32_e32 v36, v0, v0
	ds_bpermute_b32 v36, v40, v36
	v_mad_u64_u32 v[34:35], s[0:1], s50, v49, v[20:21]
	s_mul_i32 s0, s51, 0x300
	s_nop 0
	v_add_u32_e32 v35, s0, v35
	s_waitcnt lgkmcnt(0)
	v_fmac_f32_e32 v36, v0, v0
	ds_bpermute_b32 v37, v41, v36
	v_and_or_b32 v2, v2, s88, v3
	global_store_dword v[34:35], v2, off
	v_mul_f32_e32 v2, v1, v82
	v_mul_f32_e32 v3, v1, v83
	s_waitcnt lgkmcnt(0)
	v_add_f32_e32 v36, v36, v37
	ds_bpermute_b32 v37, v42, v36
	v_bfe_u32 v38, v2, 16, 1
	v_add3_u32 v2, v2, v38, s90
	v_bfe_u32 v38, v3, 16, 1
	v_lshrrev_b32_e32 v2, 16, v2
	v_add3_u32 v3, v3, v38, s90
	v_and_or_b32 v2, v3, s88, v2
	s_waitcnt lgkmcnt(0)
	v_add_f32_e32 v3, v36, v37
	ds_bpermute_b32 v36, v43, v3
	global_store_dword v[34:35], v2, off offset:256
	v_mul_f32_e32 v2, v1, v84
	v_mul_f32_e32 v37, v1, v74
	v_bfe_u32 v1, v2, 16, 1
	v_add3_u32 v1, v2, v1, s90
	v_lshrrev_b32_e32 v38, 16, v1
	s_waitcnt lgkmcnt(0)
	v_add_f32_e32 v1, v3, v36
	ds_bpermute_b32 v2, v44, v1
	v_bfe_u32 v3, v37, 16, 1
	v_add3_u32 v3, v37, v3, s90
	v_and_or_b32 v3, v3, s88, v38
	global_store_dword v[34:35], v3, off offset:512
	s_and_saveexec_b64 s[0:1], s[4:5]
	s_cbranch_execz .LBB0_791
	s_andn2_b64 vcc, exec, s[74:75]
	s_mov_b64 s[54:55], -1
	s_cbranch_vccnz .LBB0_787
	s_mov_b32 s73, s11
	s_lshl_b64 s[12:13], s[72:73], 7
	s_add_u32 s12, s80, s12
	s_addc_u32 s13, s81, s13
	s_lshl_b64 s[52:53], s[50:51], 7
	s_mov_b64 s[54:55], 0

.LBB0_792:
	s_waitcnt lgkmcnt(0)
	v_mov_b32_e32 v0, v96
	v_mov_b32_e32 v1, v97
	v_mov_b32_e32 v2, v98
	v_mov_b32_e32 v3, v99
	v_lshlrev_b32_e32 v35, 16, v33
	v_lshlrev_b32_e32 v34, 16, v32
	v_and_b32_e32 v33, 0xffff0000, v33
	v_and_b32_e32 v32, 0xffff0000, v32
	v_pk_mul_f32 v[36:37], v[32:33], v[32:33]
	s_cmpk_gt_i32 s44, 0x3fff
	v_pk_fma_f32 v[36:37], v[34:35], v[34:35], v[36:37]
	s_cselect_b64 s[50:51], -1, 0
	v_add_f32_e32 v36, v36, v37
	ds_bpermute_b32 v37, v40, v36
	s_cmpk_lt_i32 s44, 0x4000
	s_mov_b64 s[0:1], -1
	s_waitcnt lgkmcnt(0)
	v_add_f32_e32 v36, v36, v37
	ds_bpermute_b32 v37, v41, v36
	s_waitcnt lgkmcnt(0)
	v_add_f32_e32 v36, v36, v37
	ds_bpermute_b32 v37, v42, v36
	s_waitcnt lgkmcnt(0)
	v_add_f32_e32 v36, v36, v37
	ds_bpermute_b32 v37, v43, v36
	s_waitcnt lgkmcnt(0)
	v_add_f32_e32 v36, v36, v37
	ds_bpermute_b32 v37, v44, v36
	s_waitcnt lgkmcnt(0)
	v_add_f32_e32 v36, v36, v37
	ds_bpermute_b32 v37, v45, v36
	s_cbranch_scc1 .LBB0_794
	s_mov_b32 s47, s11
	s_lshl_b64 s[0:1], s[46:47], 10
	s_add_u32 s12, s66, s0
	s_addc_u32 s13, s67, s1
	s_mov_b32 s45, s11
	s_mov_b64 s[0:1], 0

.LBB0_796:
	s_waitcnt lgkmcnt(0)
	v_add_f32_e32 v36, v36, v37
	v_fmamk_f32 v36, v36, 0x3b800000, v47
	v_mul_f32_e32 v37, 0x4f800000, v36
	v_cmp_gt_f32_e32 vcc, s89, v36
	v_lshlrev_b32_e32 v73, 16, v69
	v_and_b32_e32 v69, 0xffff0000, v69
	v_cndmask_b32_e32 v36, v36, v37, vcc
	v_sqrt_f32_e32 v37, v36
	v_mul_f32_e32 v74, v69, v69
	v_fmac_f32_e32 v74, v73, v73
	v_add_u32_e32 v38, -1, v37
	v_fma_f32 v71, -v38, v37, v36
	v_add_u32_e32 v39, 1, v37
	v_cmp_ge_f32_e64 s[0:1], 0, v71
	v_lshlrev_b32_e32 v71, 16, v70
	v_and_b32_e32 v70, 0xffff0000, v70
	v_cndmask_b32_e64 v38, v37, v38, s[0:1]
	v_fma_f32 v37, -v39, v37, v36
	v_mul_f32_e32 v72, v70, v70
	v_cmp_lt_f32_e64 s[0:1], 0, v37
	v_fmac_f32_e32 v72, v71, v71
	v_add_f32_e32 v72, v72, v74
	v_cndmask_b32_e64 v37, v38, v39, s[0:1]
	v_lshlrev_b32_e32 v74, 16, v68
	v_and_b32_e32 v68, 0xffff0000, v68
	v_mul_f32_e32 v38, 0x37800000, v37
	v_mul_f32_e32 v75, v68, v68
	v_cndmask_b32_e32 v37, v37, v38, vcc
	v_cmp_class_f32_e32 vcc, v36, v48
	v_fmac_f32_e32 v75, v74, v74
	v_add_f32_e32 v72, v72, v75
	v_cndmask_b32_e32 v36, v37, v36, vcc
	v_div_scale_f32 v37, s[0:1], v36, v36, 1.0
	ds_bpermute_b32 v75, v40, v72
	v_rcp_f32_e32 v38, v37
	s_waitcnt lgkmcnt(0)
	v_add_f32_e32 v72, v72, v75
	v_fma_f32 v39, -v37, v38, 1.0
	v_fmac_f32_e32 v38, v39, v38
	v_div_scale_f32 v39, vcc, 1.0, v36, 1.0
	ds_bpermute_b32 v75, v41, v72
	v_mul_f32_e32 v76, v39, v38
	v_fma_f32 v77, -v37, v76, v39
	v_fmac_f32_e32 v76, v77, v38
	v_fma_f32 v37, -v37, v76, v39
	v_div_fmas_f32 v37, v37, v38, v76
	v_mov_b32_e32 v38, v34
	s_waitcnt lgkmcnt(0)
	v_add_f32_e32 v34, v72, v75
	v_div_fixup_f32 v36, v37, v36, 1.0
	ds_bpermute_b32 v37, v42, v34
	v_mov_b32_e32 v39, v32
	v_mov_b32_e32 v32, v35
	s_waitcnt lgkmcnt(0)
	v_add_f32_e32 v34, v34, v37
	ds_bpermute_b32 v35, v43, v34
	v_pk_mul_f32 v[38:39], v[36:37], v[38:39] op_sel_hi:[0,1]
	v_pk_mul_f32 v[32:33], v[36:37], v[32:33] op_sel_hi:[0,1]
	v_pk_mul_f32 v[2:3], v[2:3], v[32:33]
	v_pk_mul_f32 v[0:1], v[0:1], v[38:39]
	v_lshl_add_u64 v[32:33], v[6:7], 2, s[12:13]
	global_store_dwordx4 v[32:33], v[0:3], off
	s_waitcnt lgkmcnt(0)
	v_add_f32_e32 v33, v34, v35
	ds_bpermute_b32 v34, v44, v33
	v_bfe_u32 v32, v0, 16, 1
	v_add3_u32 v0, v0, v32, s90
	v_bfe_u32 v32, v1, 16, 1
	v_add3_u32 v1, v1, v32, s90
	s_waitcnt lgkmcnt(0)
	v_add_f32_e32 v32, v33, v34
	ds_bpermute_b32 v33, v45, v32
	v_lshrrev_b32_e32 v0, 16, v0
	v_and_or_b32 v0, v1, s88, v0
	v_bfe_u32 v1, v2, 16, 1
	v_add3_u32 v1, v2, v1, s90
	s_waitcnt lgkmcnt(0)
	v_add_f32_e32 v2, v32, v33
	v_fmamk_f32 v2, v2, 0x3b2aaaab, v47
	v_mul_f32_e32 v32, 0x4f800000, v2
	v_cmp_gt_f32_e32 vcc, s89, v2
	v_bfe_u32 v33, v3, 16, 1
	v_lshrrev_b32_e32 v1, 16, v1
	v_cndmask_b32_e32 v2, v2, v32, vcc
	v_sqrt_f32_e32 v32, v2
	v_add3_u32 v3, v3, v33, s90
	v_and_or_b32 v1, v3, s88, v1
	v_add_u32_e32 v3, -1, v32
	v_fma_f32 v33, -v3, v32, v2
	v_cmp_ge_f32_e64 s[0:1], 0, v33
	v_add_u32_e32 v33, 1, v32
	s_nop 0
	v_cndmask_b32_e64 v3, v32, v3, s[0:1]
	v_fma_f32 v32, -v33, v32, v2
	v_cmp_lt_f32_e64 s[0:1], 0, v32
	s_nop 1
	v_cndmask_b32_e64 v3, v3, v33, s[0:1]
	v_mul_f32_e32 v32, 0x37800000, v3
	v_cndmask_b32_e32 v3, v3, v32, vcc
	v_cmp_class_f32_e32 vcc, v2, v48
	s_nop 1
	v_cndmask_b32_e32 v32, v3, v2, vcc
	v_div_scale_f32 v33, s[0:1], v32, v32, 1.0
	v_rcp_f32_e32 v34, v33
	s_lshl_b64 s[0:1], s[44:45], 9
	v_lshl_add_u64 v[2:3], v[16:17], 0, s[0:1]
	global_store_dwordx2 v[2:3], v[0:1], off
	v_fma_f32 v0, -v33, v34, 1.0
	v_fmac_f32_e32 v34, v0, v34
	v_div_scale_f32 v0, vcc, 1.0, v32, 1.0
	v_mul_f32_e32 v1, v0, v34
	v_fma_f32 v2, -v33, v1, v0
	v_fmac_f32_e32 v1, v2, v34
	v_fma_f32 v0, -v33, v1, v0
	v_div_fmas_f32 v0, v0, v34, v1
	v_div_fixup_f32 v1, v0, v32, 1.0
	v_mul_f32_e32 v0, v1, v71
	v_bfe_u32 v3, v0, 16, 1
	v_mul_f32_e32 v2, v1, v70
	v_add3_u32 v0, v0, v3, s90
	v_lshrrev_b32_e32 v3, 16, v0
	v_bfe_u32 v0, v2, 16, 1
	v_lshlrev_b32_e32 v34, 16, v67
	v_add3_u32 v2, v2, v0, s90
	v_lshlrev_b32_e32 v0, 16, v66
	v_mul_f32_e32 v35, v64, v34
	v_mul_f32_e32 v34, v65, v34
	v_fma_f32 v35, v65, v0, -v35
	v_fmac_f32_e32 v34, v64, v0
	v_cndmask_b32_e64 v0, v34, v35, s[2:3]
	v_mul_f32_e32 v34, v0, v0
	ds_bpermute_b32 v34, v40, v34
	v_mad_u64_u32 v[32:33], s[0:1], s44, v49, v[20:21]
	s_mul_i32 s0, s45, 0x300
	s_nop 0
	v_add_u32_e32 v33, s0, v33
	s_waitcnt lgkmcnt(0)
	v_fmac_f32_e32 v34, v0, v0
	ds_bpermute_b32 v35, v41, v34
	v_and_or_b32 v2, v2, s88, v3
	global_store_dword v[32:33], v2, off
	v_mul_f32_e32 v2, v1, v73
	v_mul_f32_e32 v3, v1, v69
	s_waitcnt lgkmcnt(0)
	v_add_f32_e32 v34, v34, v35
	ds_bpermute_b32 v35, v42, v34
	v_bfe_u32 v36, v2, 16, 1
	v_add3_u32 v2, v2, v36, s90
	v_bfe_u32 v36, v3, 16, 1
	v_lshrrev_b32_e32 v2, 16, v2
	v_add3_u32 v3, v3, v36, s90
	v_and_or_b32 v2, v3, s88, v2
	s_waitcnt lgkmcnt(0)
	v_add_f32_e32 v3, v34, v35
	ds_bpermute_b32 v34, v43, v3
	global_store_dword v[32:33], v2, off offset:256
	v_mul_f32_e32 v2, v1, v74
	v_mul_f32_e32 v35, v1, v68
	v_bfe_u32 v1, v2, 16, 1
	v_add3_u32 v1, v2, v1, s90
	v_lshrrev_b32_e32 v36, 16, v1
	s_waitcnt lgkmcnt(0)
	v_add_f32_e32 v1, v3, v34
	ds_bpermute_b32 v2, v44, v1
	v_bfe_u32 v3, v35, 16, 1
	v_add3_u32 v3, v35, v3, s90
	v_and_or_b32 v3, v3, s88, v36
	global_store_dword v[32:33], v3, off offset:512
	s_and_saveexec_b64 s[0:1], s[4:5]
	s_cbranch_execz .LBB0_803
	s_andn2_b64 vcc, exec, s[50:51]
	s_mov_b64 s[52:53], -1
	s_cbranch_vccnz .LBB0_799
	s_mov_b32 s47, s11
	s_lshl_b64 s[12:13], s[46:47], 7
	s_add_u32 s12, s80, s12
	s_addc_u32 s13, s81, s13
	s_lshl_b64 s[50:51], s[44:45], 7
	s_mov_b64 s[52:53], 0

.LBB0_804:
	s_waitcnt lgkmcnt(0)
	v_mov_b32_e32 v0, v96
	v_mov_b32_e32 v1, v97
	v_mov_b32_e32 v2, v98
	v_mov_b32_e32 v3, v99
	v_lshlrev_b32_e32 v33, 16, v31
	v_lshlrev_b32_e32 v32, 16, v30
	v_and_b32_e32 v31, 0xffff0000, v31
	v_and_b32_e32 v30, 0xffff0000, v30
	v_pk_mul_f32 v[34:35], v[30:31], v[30:31]
	s_cmpk_gt_i32 s38, 0x3fff
	v_pk_fma_f32 v[34:35], v[32:33], v[32:33], v[34:35]
	s_cselect_b64 s[44:45], -1, 0
	v_add_f32_e32 v34, v34, v35
	ds_bpermute_b32 v35, v40, v34
	s_cmpk_lt_i32 s38, 0x4000
	s_mov_b64 s[0:1], -1
	s_waitcnt lgkmcnt(0)
	v_add_f32_e32 v34, v34, v35
	ds_bpermute_b32 v35, v41, v34
	s_waitcnt lgkmcnt(0)
	v_add_f32_e32 v34, v34, v35
	ds_bpermute_b32 v35, v42, v34
	s_waitcnt lgkmcnt(0)
	v_add_f32_e32 v34, v34, v35
	ds_bpermute_b32 v35, v43, v34
	s_waitcnt lgkmcnt(0)
	v_add_f32_e32 v34, v34, v35
	ds_bpermute_b32 v35, v44, v34
	s_waitcnt lgkmcnt(0)
	v_add_f32_e32 v34, v34, v35
	ds_bpermute_b32 v35, v45, v34
	s_cbranch_scc1 .LBB0_806
	s_mov_b32 s41, s11
	s_lshl_b64 s[0:1], s[40:41], 10
	s_add_u32 s12, s66, s0
	s_addc_u32 s13, s67, s1
	s_mov_b32 s39, s11
	s_mov_b64 s[0:1], 0

.LBB0_808:
	s_waitcnt lgkmcnt(0)
	v_add_f32_e32 v34, v34, v35
	v_fmamk_f32 v34, v34, 0x3b800000, v47
	v_mul_f32_e32 v35, 0x4f800000, v34
	v_cmp_gt_f32_e32 vcc, s89, v34
	v_and_b32_e32 v39, 0xffff0000, v63
	v_lshlrev_b32_e32 v64, 16, v62
	v_cndmask_b32_e32 v34, v34, v35, vcc
	v_sqrt_f32_e32 v35, v34
	v_and_b32_e32 v62, 0xffff0000, v62
	v_mul_f32_e32 v65, v62, v62
	v_fmac_f32_e32 v65, v64, v64
	v_add_u32_e32 v36, -1, v35
	v_fma_f32 v38, -v36, v35, v34
	v_add_u32_e32 v37, 1, v35
	v_cmp_ge_f32_e64 s[0:1], 0, v38
	v_lshlrev_b32_e32 v38, 16, v63
	v_mul_f32_e32 v63, v39, v39
	v_cndmask_b32_e64 v36, v35, v36, s[0:1]
	v_fma_f32 v35, -v37, v35, v34
	v_cmp_lt_f32_e64 s[0:1], 0, v35
	v_fmac_f32_e32 v63, v38, v38
	v_add_f32_e32 v63, v63, v65
	v_cndmask_b32_e64 v35, v36, v37, s[0:1]
	v_lshlrev_b32_e32 v65, 16, v61
	v_and_b32_e32 v61, 0xffff0000, v61
	v_mul_f32_e32 v36, 0x37800000, v35
	v_mul_f32_e32 v66, v61, v61
	v_cndmask_b32_e32 v35, v35, v36, vcc
	v_cmp_class_f32_e32 vcc, v34, v48
	v_fmac_f32_e32 v66, v65, v65
	v_add_f32_e32 v63, v63, v66
	v_cndmask_b32_e32 v34, v35, v34, vcc
	v_div_scale_f32 v35, s[0:1], v34, v34, 1.0
	ds_bpermute_b32 v66, v40, v63
	v_rcp_f32_e32 v36, v35
	s_waitcnt lgkmcnt(0)
	v_add_f32_e32 v63, v63, v66
	v_fma_f32 v37, -v35, v36, 1.0
	v_fmac_f32_e32 v36, v37, v36
	v_div_scale_f32 v37, vcc, 1.0, v34, 1.0
	ds_bpermute_b32 v66, v41, v63
	v_mul_f32_e32 v67, v37, v36
	v_fma_f32 v68, -v35, v67, v37
	v_fmac_f32_e32 v67, v68, v36
	v_fma_f32 v35, -v35, v67, v37
	v_div_fmas_f32 v35, v35, v36, v67
	v_mov_b32_e32 v36, v32
	s_waitcnt lgkmcnt(0)
	v_add_f32_e32 v32, v63, v66
	v_div_fixup_f32 v34, v35, v34, 1.0
	ds_bpermute_b32 v35, v42, v32
	v_mov_b32_e32 v37, v30
	v_mov_b32_e32 v30, v33
	s_waitcnt lgkmcnt(0)
	v_add_f32_e32 v32, v32, v35
	ds_bpermute_b32 v33, v43, v32
	v_pk_mul_f32 v[36:37], v[34:35], v[36:37] op_sel_hi:[0,1]
	v_pk_mul_f32 v[30:31], v[34:35], v[30:31] op_sel_hi:[0,1]
	v_pk_mul_f32 v[2:3], v[2:3], v[30:31]
	v_pk_mul_f32 v[0:1], v[0:1], v[36:37]
	v_lshl_add_u64 v[30:31], v[6:7], 2, s[12:13]
	global_store_dwordx4 v[30:31], v[0:3], off
	s_waitcnt lgkmcnt(0)
	v_add_f32_e32 v31, v32, v33
	ds_bpermute_b32 v32, v44, v31
	v_bfe_u32 v30, v0, 16, 1
	v_add3_u32 v0, v0, v30, s90
	v_bfe_u32 v30, v1, 16, 1
	v_add3_u32 v1, v1, v30, s90
	s_waitcnt lgkmcnt(0)
	v_add_f32_e32 v30, v31, v32
	ds_bpermute_b32 v31, v45, v30
	v_lshrrev_b32_e32 v0, 16, v0
	v_and_or_b32 v0, v1, s88, v0
	v_bfe_u32 v1, v2, 16, 1
	v_add3_u32 v1, v2, v1, s90
	s_waitcnt lgkmcnt(0)
	v_add_f32_e32 v2, v30, v31
	v_fmamk_f32 v2, v2, 0x3b2aaaab, v47
	v_mul_f32_e32 v30, 0x4f800000, v2
	v_cmp_gt_f32_e32 vcc, s89, v2
	v_bfe_u32 v31, v3, 16, 1
	v_lshrrev_b32_e32 v1, 16, v1
	v_cndmask_b32_e32 v2, v2, v30, vcc
	v_sqrt_f32_e32 v30, v2
	v_add3_u32 v3, v3, v31, s90
	v_and_or_b32 v1, v3, s88, v1
	v_add_u32_e32 v3, -1, v30
	v_fma_f32 v31, -v3, v30, v2
	v_cmp_ge_f32_e64 s[0:1], 0, v31
	v_add_u32_e32 v31, 1, v30
	s_nop 0
	v_cndmask_b32_e64 v3, v30, v3, s[0:1]
	v_fma_f32 v30, -v31, v30, v2
	v_cmp_lt_f32_e64 s[0:1], 0, v30
	s_nop 1
	v_cndmask_b32_e64 v3, v3, v31, s[0:1]
	v_mul_f32_e32 v30, 0x37800000, v3
	v_cndmask_b32_e32 v3, v3, v30, vcc
	v_cmp_class_f32_e32 vcc, v2, v48
	s_nop 1
	v_cndmask_b32_e32 v30, v3, v2, vcc
	v_div_scale_f32 v31, s[0:1], v30, v30, 1.0
	v_rcp_f32_e32 v32, v31
	s_lshl_b64 s[0:1], s[38:39], 9
	v_lshl_add_u64 v[2:3], v[16:17], 0, s[0:1]
	global_store_dwordx2 v[2:3], v[0:1], off
	v_fma_f32 v0, -v31, v32, 1.0
	v_fmac_f32_e32 v32, v0, v32
	v_div_scale_f32 v0, vcc, 1.0, v30, 1.0
	v_mul_f32_e32 v1, v0, v32
	v_fma_f32 v2, -v31, v1, v0
	v_fmac_f32_e32 v1, v2, v32
	v_fma_f32 v0, -v31, v1, v0
	v_div_fmas_f32 v0, v0, v32, v1
	v_div_fixup_f32 v1, v0, v30, 1.0
	v_mul_f32_e32 v0, v1, v38
	v_bfe_u32 v3, v0, 16, 1
	v_mul_f32_e32 v2, v1, v39
	v_add3_u32 v0, v0, v3, s90
	v_lshrrev_b32_e32 v3, 16, v0
	v_bfe_u32 v0, v2, 16, 1
	v_lshlrev_b32_e32 v32, 16, v60
	v_add3_u32 v2, v2, v0, s90
	v_lshlrev_b32_e32 v0, 16, v59
	v_mul_f32_e32 v33, v57, v32
	v_mul_f32_e32 v32, v58, v32
	v_fma_f32 v33, v58, v0, -v33
	v_fmac_f32_e32 v32, v57, v0
	v_cndmask_b32_e64 v0, v32, v33, s[2:3]
	v_mul_f32_e32 v32, v0, v0
	ds_bpermute_b32 v32, v40, v32
	v_mad_u64_u32 v[30:31], s[0:1], s38, v49, v[20:21]
	s_mul_i32 s0, s39, 0x300
	s_nop 0
	v_add_u32_e32 v31, s0, v31
	s_waitcnt lgkmcnt(0)
	v_fmac_f32_e32 v32, v0, v0
	ds_bpermute_b32 v33, v41, v32
	v_and_or_b32 v2, v2, s88, v3
	global_store_dword v[30:31], v2, off
	v_mul_f32_e32 v2, v1, v64
	v_mul_f32_e32 v3, v1, v62
	s_waitcnt lgkmcnt(0)
	v_add_f32_e32 v32, v32, v33
	ds_bpermute_b32 v33, v42, v32
	v_bfe_u32 v34, v2, 16, 1
	v_add3_u32 v2, v2, v34, s90
	v_bfe_u32 v34, v3, 16, 1
	v_lshrrev_b32_e32 v2, 16, v2
	v_add3_u32 v3, v3, v34, s90
	v_and_or_b32 v2, v3, s88, v2
	s_waitcnt lgkmcnt(0)
	v_add_f32_e32 v3, v32, v33
	ds_bpermute_b32 v32, v43, v3
	global_store_dword v[30:31], v2, off offset:256
	v_mul_f32_e32 v2, v1, v65
	v_mul_f32_e32 v33, v1, v61
	v_bfe_u32 v1, v2, 16, 1
	v_add3_u32 v1, v2, v1, s90
	v_lshrrev_b32_e32 v34, 16, v1
	s_waitcnt lgkmcnt(0)
	v_add_f32_e32 v1, v3, v32
	ds_bpermute_b32 v2, v44, v1
	v_bfe_u32 v3, v33, 16, 1
	v_add3_u32 v3, v33, v3, s90
	v_and_or_b32 v3, v3, s88, v34
	global_store_dword v[30:31], v3, off offset:512
	s_and_saveexec_b64 s[0:1], s[4:5]
	s_cbranch_execz .LBB0_815
	s_andn2_b64 vcc, exec, s[44:45]
	s_mov_b64 s[46:47], -1
	s_cbranch_vccnz .LBB0_811
	s_mov_b32 s41, s11
	s_lshl_b64 s[12:13], s[40:41], 7
	s_add_u32 s12, s80, s12
	s_addc_u32 s13, s81, s13
	s_lshl_b64 s[44:45], s[38:39], 7
	s_mov_b64 s[46:47], 0

.LBB0_816:
	s_waitcnt lgkmcnt(0)
	v_mov_b32_e32 v0, v96
	v_mov_b32_e32 v1, v97
	v_mov_b32_e32 v2, v98
	v_mov_b32_e32 v3, v99
	v_lshlrev_b32_e32 v31, 16, v29
	v_lshlrev_b32_e32 v30, 16, v28
	v_and_b32_e32 v29, 0xffff0000, v29
	v_and_b32_e32 v28, 0xffff0000, v28
	v_pk_mul_f32 v[32:33], v[28:29], v[28:29]
	s_cmpk_gt_i32 s34, 0x3fff
	v_pk_fma_f32 v[32:33], v[30:31], v[30:31], v[32:33]
	s_cselect_b64 s[38:39], -1, 0
	v_add_f32_e32 v32, v32, v33
	ds_bpermute_b32 v33, v40, v32
	s_cmpk_lt_i32 s34, 0x4000
	s_mov_b64 s[0:1], -1
	s_waitcnt lgkmcnt(0)
	v_add_f32_e32 v32, v32, v33
	ds_bpermute_b32 v33, v41, v32
	s_waitcnt lgkmcnt(0)
	v_add_f32_e32 v32, v32, v33
	ds_bpermute_b32 v33, v42, v32
	s_waitcnt lgkmcnt(0)
	v_add_f32_e32 v32, v32, v33
	ds_bpermute_b32 v33, v43, v32
	s_waitcnt lgkmcnt(0)
	v_add_f32_e32 v32, v32, v33
	ds_bpermute_b32 v33, v44, v32
	s_waitcnt lgkmcnt(0)
	v_add_f32_e32 v32, v32, v33
	ds_bpermute_b32 v33, v45, v32
	s_cbranch_scc1 .LBB0_818
	s_mov_b32 s37, s11
	s_lshl_b64 s[0:1], s[36:37], 10
	s_add_u32 s12, s66, s0
	s_addc_u32 s13, s67, s1
	s_mov_b32 s35, s11
	s_mov_b64 s[0:1], 0

.LBB0_820:
	s_waitcnt lgkmcnt(0)
	v_add_f32_e32 v32, v32, v33
	v_fmamk_f32 v32, v32, 0x3b800000, v47
	v_mul_f32_e32 v33, 0x4f800000, v32
	v_cmp_gt_f32_e32 vcc, s89, v32
	v_and_b32_e32 v37, 0xffff0000, v56
	v_lshlrev_b32_e32 v39, 16, v55
	v_cndmask_b32_e32 v32, v32, v33, vcc
	v_sqrt_f32_e32 v33, v32
	v_and_b32_e32 v55, 0xffff0000, v55
	v_mul_f32_e32 v38, v37, v37
	v_add_u32_e32 v34, -1, v33
	v_fma_f32 v36, -v34, v33, v32
	v_add_u32_e32 v35, 1, v33
	v_cmp_ge_f32_e64 s[0:1], 0, v36
	v_lshlrev_b32_e32 v36, 16, v56
	v_mul_f32_e32 v56, v55, v55
	v_cndmask_b32_e64 v34, v33, v34, s[0:1]
	v_fma_f32 v33, -v35, v33, v32
	v_cmp_lt_f32_e64 s[0:1], 0, v33
	v_fmac_f32_e32 v38, v36, v36
	v_fmac_f32_e32 v56, v39, v39
	v_cndmask_b32_e64 v33, v34, v35, s[0:1]
	v_add_f32_e32 v38, v38, v56
	v_lshlrev_b32_e32 v56, 16, v54
	v_and_b32_e32 v54, 0xffff0000, v54
	v_mul_f32_e32 v34, 0x37800000, v33
	v_mul_f32_e32 v57, v54, v54
	v_cndmask_b32_e32 v33, v33, v34, vcc
	v_cmp_class_f32_e32 vcc, v32, v48
	v_fmac_f32_e32 v57, v56, v56
	v_add_f32_e32 v38, v38, v57
	v_cndmask_b32_e32 v32, v33, v32, vcc
	v_div_scale_f32 v33, s[0:1], v32, v32, 1.0
	ds_bpermute_b32 v57, v40, v38
	v_rcp_f32_e32 v34, v33
	s_waitcnt lgkmcnt(0)
	v_add_f32_e32 v38, v38, v57
	v_fma_f32 v35, -v33, v34, 1.0
	v_fmac_f32_e32 v34, v35, v34
	v_div_scale_f32 v35, vcc, 1.0, v32, 1.0
	ds_bpermute_b32 v57, v41, v38
	v_mul_f32_e32 v58, v35, v34
	v_fma_f32 v59, -v33, v58, v35
	v_fmac_f32_e32 v58, v59, v34
	v_fma_f32 v33, -v33, v58, v35
	v_div_fmas_f32 v33, v33, v34, v58
	v_mov_b32_e32 v34, v30
	s_waitcnt lgkmcnt(0)
	v_add_f32_e32 v30, v38, v57
	v_div_fixup_f32 v32, v33, v32, 1.0
	ds_bpermute_b32 v33, v42, v30
	v_mov_b32_e32 v35, v28
	v_mov_b32_e32 v28, v31
	s_waitcnt lgkmcnt(0)
	v_add_f32_e32 v30, v30, v33
	ds_bpermute_b32 v31, v43, v30
	v_pk_mul_f32 v[34:35], v[32:33], v[34:35] op_sel_hi:[0,1]
	v_pk_mul_f32 v[28:29], v[32:33], v[28:29] op_sel_hi:[0,1]
	v_pk_mul_f32 v[2:3], v[2:3], v[28:29]
	v_pk_mul_f32 v[0:1], v[0:1], v[34:35]
	v_lshl_add_u64 v[28:29], v[6:7], 2, s[12:13]
	global_store_dwordx4 v[28:29], v[0:3], off
	s_waitcnt lgkmcnt(0)
	v_add_f32_e32 v29, v30, v31
	ds_bpermute_b32 v30, v44, v29
	v_bfe_u32 v28, v0, 16, 1
	v_add3_u32 v0, v0, v28, s90
	v_bfe_u32 v28, v1, 16, 1
	v_add3_u32 v1, v1, v28, s90
	s_waitcnt lgkmcnt(0)
	v_add_f32_e32 v28, v29, v30
	ds_bpermute_b32 v29, v45, v28
	v_lshrrev_b32_e32 v0, 16, v0
	v_and_or_b32 v0, v1, s88, v0
	v_bfe_u32 v1, v2, 16, 1
	v_add3_u32 v1, v2, v1, s90
	s_waitcnt lgkmcnt(0)
	v_add_f32_e32 v2, v28, v29
	v_fmamk_f32 v2, v2, 0x3b2aaaab, v47
	v_mul_f32_e32 v28, 0x4f800000, v2
	v_cmp_gt_f32_e32 vcc, s89, v2
	v_bfe_u32 v29, v3, 16, 1
	v_lshrrev_b32_e32 v1, 16, v1
	v_cndmask_b32_e32 v2, v2, v28, vcc
	v_sqrt_f32_e32 v28, v2
	v_add3_u32 v3, v3, v29, s90
	v_and_or_b32 v1, v3, s88, v1
	v_add_u32_e32 v3, -1, v28
	v_fma_f32 v29, -v3, v28, v2
	v_cmp_ge_f32_e64 s[0:1], 0, v29
	v_add_u32_e32 v29, 1, v28
	s_nop 0
	v_cndmask_b32_e64 v3, v28, v3, s[0:1]
	v_fma_f32 v28, -v29, v28, v2
	v_cmp_lt_f32_e64 s[0:1], 0, v28
	s_nop 1
	v_cndmask_b32_e64 v3, v3, v29, s[0:1]
	v_mul_f32_e32 v28, 0x37800000, v3
	v_cndmask_b32_e32 v3, v3, v28, vcc
	v_cmp_class_f32_e32 vcc, v2, v48
	s_nop 1
	v_cndmask_b32_e32 v28, v3, v2, vcc
	v_div_scale_f32 v29, s[0:1], v28, v28, 1.0
	v_rcp_f32_e32 v30, v29
	s_lshl_b64 s[0:1], s[34:35], 9
	v_lshl_add_u64 v[2:3], v[16:17], 0, s[0:1]
	global_store_dwordx2 v[2:3], v[0:1], off
	v_fma_f32 v0, -v29, v30, 1.0
	v_fmac_f32_e32 v30, v0, v30
	v_div_scale_f32 v0, vcc, 1.0, v28, 1.0
	v_mul_f32_e32 v1, v0, v30
	v_fma_f32 v2, -v29, v1, v0
	v_fmac_f32_e32 v1, v2, v30
	v_fma_f32 v0, -v29, v1, v0
	v_div_fmas_f32 v0, v0, v30, v1
	v_div_fixup_f32 v1, v0, v28, 1.0
	v_mul_f32_e32 v0, v1, v36
	v_bfe_u32 v3, v0, 16, 1
	v_mul_f32_e32 v2, v1, v37
	v_add3_u32 v0, v0, v3, s90
	v_lshrrev_b32_e32 v3, 16, v0
	v_bfe_u32 v0, v2, 16, 1
	v_lshlrev_b32_e32 v30, 16, v51
	v_add3_u32 v2, v2, v0, s90
	v_lshlrev_b32_e32 v0, 16, v50
	v_mul_f32_e32 v31, v52, v30
	v_mul_f32_e32 v30, v53, v30
	v_fma_f32 v31, v53, v0, -v31
	v_fmac_f32_e32 v30, v52, v0
	v_cndmask_b32_e64 v0, v30, v31, s[2:3]
	v_mul_f32_e32 v30, v0, v0
	ds_bpermute_b32 v30, v40, v30
	v_mad_u64_u32 v[28:29], s[0:1], s34, v49, v[20:21]
	s_mul_i32 s0, s35, 0x300
	s_nop 0
	v_add_u32_e32 v29, s0, v29
	s_waitcnt lgkmcnt(0)
	v_fmac_f32_e32 v30, v0, v0
	ds_bpermute_b32 v31, v41, v30
	v_and_or_b32 v2, v2, s88, v3
	global_store_dword v[28:29], v2, off
	v_mul_f32_e32 v2, v1, v39
	v_mul_f32_e32 v3, v1, v55
	s_waitcnt lgkmcnt(0)
	v_add_f32_e32 v30, v30, v31
	ds_bpermute_b32 v31, v42, v30
	v_bfe_u32 v32, v2, 16, 1
	v_add3_u32 v2, v2, v32, s90
	v_bfe_u32 v32, v3, 16, 1
	v_lshrrev_b32_e32 v2, 16, v2
	v_add3_u32 v3, v3, v32, s90
	v_and_or_b32 v2, v3, s88, v2
	s_waitcnt lgkmcnt(0)
	v_add_f32_e32 v3, v30, v31
	ds_bpermute_b32 v30, v43, v3
	global_store_dword v[28:29], v2, off offset:256
	v_mul_f32_e32 v2, v1, v56
	v_mul_f32_e32 v31, v1, v54
	v_bfe_u32 v1, v2, 16, 1
	v_add3_u32 v1, v2, v1, s90
	v_lshrrev_b32_e32 v32, 16, v1
	s_waitcnt lgkmcnt(0)
	v_add_f32_e32 v1, v3, v30
	ds_bpermute_b32 v2, v44, v1
	v_bfe_u32 v3, v31, 16, 1
	v_add3_u32 v3, v31, v3, s90
	v_and_or_b32 v3, v3, s88, v32
	global_store_dword v[28:29], v3, off offset:512
	s_and_saveexec_b64 s[0:1], s[4:5]
	s_cbranch_execz .LBB0_763
	s_andn2_b64 vcc, exec, s[38:39]
	s_mov_b64 s[40:41], -1
	s_cbranch_vccnz .LBB0_823
	s_mov_b32 s37, s11
	s_lshl_b64 s[12:13], s[36:37], 7
	s_add_u32 s12, s80, s12
	s_addc_u32 s13, s81, s13
	s_lshl_b64 s[38:39], s[34:35], 7
	s_mov_b64 s[40:41], 0
